# rwpost output rows also stored write-through (sc1) ahead of the phase 5->6 grid barrier
# speedup vs baseline: 1.0169x; 1.0012x over previous
; __device__ __forceinline__ float red8(float x) { x = red4(x); x += dppf<0x141>(x); return x; }
; __device__ __forceinline__ float red16(float x) { x = red8(x); x += dppf<0x140>(x); return x; }
; __device__ __forceinline__ void ph_rwpost(const Params& p) {
;     ...
;     for (; row < NTOK; row += nw) {
;         const int nr = row + nw;
;         if (nr < NTOK) RP_LD(nxt, nr);
;         float y[8], r[8], k[8], v[8], g[8], ho[8], hg[8];
;         unpack8(cur[0], y); unpack8(cur[1], r); unpack8(cur[2], k); unpack8(cur[3], v); unpack8(cur[4], g); unpack8(cur[5], ho); unpack8(cur[6], hg);
;         float s = 0.f, bs = 0.f, hs = 0.f;
; #pragma unroll
;         for (int j = 0; j < 8; ++j) { s += y[j]; bs += r[j] * k[j] * rk[j]; hs += ho[j] * ho[j]; }
;         s = red8(s); bs = red8(bs); hs = red16(hs); const float mean = s * (1.0f / 64.0f); float q = 0.f;
; #pragma unroll
;         for (int j = 0; j < 8; ++j) { const float d = y[j] - mean; q += d * d; }
;         q = red8(q); const float rstd = rsqrtf(q * (1.0f / 64.0f) + 64e-5f); const float hrs = rsqrtf(hs * (1.0f / 128.0f) + 1e-6f); float out[8], hout[8];
.LBB0_832:
	s_or_b64 exec, exec, s[0:1]
	s_waitcnt vmcnt(5)
	v_and_b32_e32 v103, 0xffff0000, v80
	v_lshlrev_b32_e32 v102, 16, v80
	s_waitcnt vmcnt(4)
	v_and_b32_e32 v105, 0xffff0000, v84
	v_lshlrev_b32_e32 v104, 16, v84
	v_pk_mul_f32 v[102:103], v[102:103], v[104:105]
	v_lshlrev_b32_e32 v108, 16, v68
	v_pk_mul_f32 v[102:103], v[0:1], v[102:103]
	s_waitcnt vmcnt(0)
	v_lshlrev_b32_e32 v128, 16, v65
	v_add_f32_e32 v80, 0, v102
	v_add_f32_e32 v84, v103, v80
	v_and_b32_e32 v103, 0xffff0000, v81
	v_lshlrev_b32_e32 v102, 16, v81
	v_and_b32_e32 v81, 0xffff0000, v85
	v_lshlrev_b32_e32 v80, 16, v85
	v_pk_mul_f32 v[80:81], v[102:103], v[80:81]
	v_and_b32_e32 v85, 0xffff0000, v86
	v_pk_mul_f32 v[80:81], v[2:3], v[80:81]
	v_lshlrev_b32_e32 v102, 16, v70
	v_add_f32_e32 v80, v80, v84
	v_add_f32_e32 v89, v81, v80
	v_and_b32_e32 v81, 0xffff0000, v82
	v_lshlrev_b32_e32 v80, 16, v82
	v_lshlrev_b32_e32 v84, 16, v86
	v_pk_mul_f32 v[80:81], v[80:81], v[84:85]
	v_lshlrev_b32_e32 v82, 16, v87
	v_pk_mul_f32 v[80:81], v[16:17], v[80:81]
	v_and_b32_e32 v85, 0xffff0000, v75
	v_add_f32_e32 v80, v80, v89
	v_add_f32_e32 v84, v81, v80
	v_and_b32_e32 v81, 0xffff0000, v83
	v_lshlrev_b32_e32 v80, 16, v83
	v_and_b32_e32 v83, 0xffff0000, v87
	v_pk_mul_f32 v[80:81], v[80:81], v[82:83]
	v_lshlrev_b32_e32 v82, 16, v71
	v_pk_mul_f32 v[80:81], v[18:19], v[80:81]
	v_and_b32_e32 v83, 0xffff0000, v71
	v_add_f32_e32 v80, v80, v84
	v_lshlrev_b32_e32 v84, 16, v75
	v_lshlrev_b32_e32 v86, 16, v79
	v_and_b32_e32 v87, 0xffff0000, v79
	v_and_b32_e32 v103, 0xffff0000, v70
	v_lshlrev_b32_e32 v70, 16, v74
	v_and_b32_e32 v71, 0xffff0000, v74
	v_lshlrev_b32_e32 v74, 16, v78
	v_and_b32_e32 v75, 0xffff0000, v78
	v_lshlrev_b32_e32 v78, 16, v69
	v_and_b32_e32 v79, 0xffff0000, v69
	v_lshlrev_b32_e32 v104, 16, v73
	v_and_b32_e32 v105, 0xffff0000, v73
	v_and_b32_e32 v109, 0xffff0000, v68
	v_lshlrev_b32_e32 v68, 16, v72
	v_and_b32_e32 v69, 0xffff0000, v72
	v_lshlrev_b32_e32 v72, 16, v76
	v_and_b32_e32 v73, 0xffff0000, v76
	v_add_f32_e32 v76, 0, v108
	v_lshlrev_b32_e32 v122, 16, v62
	v_and_b32_e32 v123, 0xffff0000, v62
	v_lshlrev_b32_e32 v62, 16, v66
	v_lshlrev_b32_e32 v126, 16, v61
	v_and_b32_e32 v127, 0xffff0000, v61
	v_and_b32_e32 v129, 0xffff0000, v65
	v_mul_f32_e32 v61, 0xbfb8aa3b, v128
	v_add_f32_e32 v76, v76, v109
	v_lshlrev_b32_e32 v116, 16, v63
	v_and_b32_e32 v117, 0xffff0000, v63
	v_and_b32_e32 v63, 0xffff0000, v66
	v_mul_f32_e32 v66, 0xbfb8aa3b, v62
	v_exp_f32_e32 v61, v61
	v_mul_f32_e32 v65, 0xbfb8aa3b, v129
	v_add_f32_e32 v80, v81, v80
	v_add_f32_e32 v76, v76, v78
	v_exp_f32_e32 v81, v66
	v_mul_f32_e32 v66, 0xbfb8aa3b, v63
	v_exp_f32_e32 v65, v65
	v_add_f32_e32 v76, v76, v79
	v_exp_f32_e32 v89, v66
	v_add_f32_e32 v76, v76, v102
	v_add_f32_e32 v76, v76, v103
	v_add_f32_e32 v61, 1.0, v61
	v_add_f32_e32 v76, v76, v82
	v_add_f32_e32 v81, 1.0, v81
	v_rcp_f32_e32 v132, v61
	v_add_f32_e32 v61, 1.0, v65
	v_lshlrev_b32_e32 v134, 16, v60
	v_and_b32_e32 v135, 0xffff0000, v60
	v_lshlrev_b32_e32 v60, 16, v64
	v_add_f32_e32 v76, v76, v83
	v_rcp_f32_e32 v124, v81
	v_add_f32_e32 v81, 1.0, v89
	v_rcp_f32_e32 v133, v61
	v_and_b32_e32 v61, 0xffff0000, v64
	v_mul_f32_e32 v65, 0xbfb8aa3b, v60
	v_add_f32_dpp v76, v76, v76 quad_perm:[1,0,3,2] row_mask:0xf bank_mask:0xf bound_ctrl:1
	v_rcp_f32_e32 v125, v81
	v_exp_f32_e32 v81, v65
	v_mul_f32_e32 v65, 0xbfb8aa3b, v61
	v_add_f32_dpp v76, v76, v76 quad_perm:[2,3,0,1] row_mask:0xf bank_mask:0xf bound_ctrl:1
	v_exp_f32_e32 v89, v65
	v_mul_f32_e32 v64, v135, v135
	v_add_f32_dpp v76, v76, v76 row_half_mirror row_mask:0xf bank_mask:0xf bound_ctrl:1
	v_mul_f32_e32 v76, 0x3c800000, v76
	v_pk_fma_f32 v[64:65], v[134:135], v[134:135], v[64:65] op_sel_hi:[1,1,0]
	v_pk_add_f32 v[108:109], v[108:109], v[76:77] op_sel_hi:[1,0] neg_lo:[0,1] neg_hi:[0,1]
	v_add_f32_e32 v65, 1.0, v81
	v_pk_mul_f32 v[110:111], v[108:109], v[108:109]
	v_pk_add_f32 v[78:79], v[78:79], v[76:77] op_sel_hi:[1,0] neg_lo:[0,1] neg_hi:[0,1]
	v_pk_mul_f32 v[130:131], v[126:127], v[126:127]
	v_rcp_f32_e32 v136, v65
	v_add_f32_e32 v65, 1.0, v89
	v_pk_mul_f32 v[112:113], v[78:79], v[78:79]
	v_rcp_f32_e32 v137, v65
	v_mov_b32_e32 v138, v130
	v_mov_b32_e32 v139, v110
	v_mov_b32_e32 v65, v111
	v_pk_add_f32 v[102:103], v[102:103], v[76:77] op_sel_hi:[1,0] neg_lo:[0,1] neg_hi:[0,1]
	v_lshlrev_b32_e32 v118, 16, v67
	v_and_b32_e32 v119, 0xffff0000, v67
	v_pk_mul_f32 v[66:67], v[122:123], v[122:123]
	v_pk_add_f32 v[64:65], v[138:139], v[64:65]
	v_pk_mov_b32 v[110:111], v[130:131], v[112:113] op_sel:[1,0]
	v_pk_mul_f32 v[114:115], v[102:103], v[102:103]
	v_pk_add_f32 v[64:65], v[110:111], v[64:65]
	v_mov_b32_e32 v112, v66
	v_lshlrev_b32_e32 v106, 16, v77
	v_and_b32_e32 v107, 0xffff0000, v77
	v_pk_add_f32 v[76:77], v[82:83], v[76:77] op_sel_hi:[1,0] neg_lo:[0,1] neg_hi:[0,1]
	v_pk_mul_f32 v[120:121], v[116:117], v[116:117]
	v_pk_add_f32 v[64:65], v[112:113], v[64:65]
	v_pk_mov_b32 v[66:67], v[66:67], v[114:115] op_sel:[1,0]
; __device__ __forceinline__ float sigmoidf_(float x) { return __builtin_amdgcn_rcpf(1.0f + __expf(-x)); }
; __device__ __forceinline__ float red8(float x) { x = red4(x); x += dppf<0x141>(x); return x; }
; __device__ __forceinline__ void ph_rwpost(const Params& p) {
;     ...
;         q = red8(q); const float rstd = rsqrtf(q * (1.0f / 64.0f) + 64e-5f); const float hrs = rsqrtf(hs * (1.0f / 128.0f) + 1e-6f); float out[8], hout[8];
; #pragma unroll
;         for (int j = 0; j < 8; ++j) { out[j] = ((y[j] - mean) * rstd * gw8[j] + gb8[j] + bs * v[j]) * g[j]; hout[j] = ho[j] * hrs * hn[j] * (hg[j] * sigmoidf_(hg[j])); }
;         *(u32x4*)(ob + (size_t)row * D + 512 + c) = pack8(out);
;         *(u32x4*)(ob + (size_t)row * D + c) = pack8(hout);
; #pragma unroll
;         for (int i = 0; i < 7; ++i) cur[i] = nxt[i];
;     }
	v_pk_mul_f32 v[82:83], v[76:77], v[76:77]
	v_pk_add_f32 v[64:65], v[66:67], v[64:65]
	v_mov_b32_e32 v114, v120
	v_pk_add_f32 v[64:65], v[114:115], v[64:65]
	v_pk_mov_b32 v[66:67], v[120:121], v[82:83] op_sel:[1,0]
	v_add_f32_dpp v80, v80, v80 quad_perm:[1,0,3,2] row_mask:0xf bank_mask:0xf bound_ctrl:1
	v_pk_add_f32 v[64:65], v[66:67], v[64:65]
	v_pk_mul_f32 v[60:61], v[136:137], v[60:61]
	v_add_f32_dpp v80, v80, v80 quad_perm:[2,3,0,1] row_mask:0xf bank_mask:0xf bound_ctrl:1
	v_mov_b32_dpp v82, v64 quad_perm:[1,0,3,2] row_mask:0xf bank_mask:0xf bound_ctrl:1
	v_pk_add_f32 v[64:65], v[64:65], v[82:83]
	v_add_f32_dpp v80, v80, v80 row_half_mirror row_mask:0xf bank_mask:0xf bound_ctrl:1
	v_pk_mul_f32 v[62:63], v[124:125], v[62:63]
	v_mov_b32_dpp v67, v65 quad_perm:[1,0,3,2] row_mask:0xf bank_mask:0xf bound_ctrl:1
	v_mov_b32_dpp v66, v64 quad_perm:[2,3,0,1] row_mask:0xf bank_mask:0xf bound_ctrl:1
	v_pk_add_f32 v[64:65], v[64:65], v[66:67]
	v_lshl_add_u64 v[92:93], v[92:93], 0, s[12:13]
	v_lshl_add_u64 v[94:95], v[94:95], 0, s[16:17]
	v_mov_b32_dpp v67, v65 quad_perm:[2,3,0,1] row_mask:0xf bank_mask:0xf bound_ctrl:1
	v_mov_b32_dpp v66, v64 row_half_mirror row_mask:0xf bank_mask:0xf bound_ctrl:1
	v_pk_add_f32 v[64:65], v[64:65], v[66:67]
	v_lshl_add_u64 v[96:97], v[96:97], 0, s[10:11]
	v_lshl_add_u64 v[98:99], v[98:99], 0, s[18:19]
	v_mov_b32_dpp v67, v65 row_half_mirror row_mask:0xf bank_mask:0xf bound_ctrl:1
	v_mov_b32_dpp v66, v64 row_mirror row_mask:0xf bank_mask:0xf bound_ctrl:1
	v_pk_add_f32 v[64:65], v[64:65], v[66:67]
	s_nop 0
	v_pk_fma_f32 v[64:65], v[64:65], s[22:23], v[100:101]
	s_nop 0
	v_mul_f32_e32 v66, 0x4b800000, v65
	v_cmp_gt_f32_e32 vcc, s15, v65
	s_nop 1
	v_cndmask_b32_e32 v65, v65, v66, vcc
	v_rsq_f32_e32 v65, v65
	v_pk_mul_f32 v[66:67], v[132:133], v[128:129]
	v_mul_f32_e32 v81, 0x45800000, v65
	v_cndmask_b32_e32 v82, v65, v81, vcc
	v_pk_mul_f32 v[108:109], v[108:109], v[82:83] op_sel_hi:[1,0]
	v_mul_f32_e32 v65, 0x4b800000, v64
	v_pk_fma_f32 v[108:109], v[4:5], v[108:109], v[20:21]
	v_cmp_gt_f32_e32 vcc, s15, v64
	v_pk_fma_f32 v[68:69], v[80:81], v[68:69], v[108:109] op_sel_hi:[0,1,1]
	v_pk_mul_f32 v[68:69], v[68:69], v[72:73]
	v_pk_mul_f32 v[72:73], v[78:79], v[82:83] op_sel_hi:[1,0]
	v_pk_mul_f32 v[78:79], v[102:103], v[82:83] op_sel_hi:[1,0]
	v_cndmask_b32_e32 v64, v64, v65, vcc
	v_pk_fma_f32 v[78:79], v[8:9], v[78:79], v[12:13]
	v_pk_fma_f32 v[72:73], v[6:7], v[72:73], v[22:23]
	v_pk_fma_f32 v[70:71], v[80:81], v[70:71], v[78:79] op_sel_hi:[0,1,1]
	v_pk_mul_f32 v[70:71], v[70:71], v[74:75]
	v_pk_mul_f32 v[74:75], v[76:77], v[82:83] op_sel_hi:[1,0]
	v_rsq_f32_e32 v76, v64
	v_pk_fma_f32 v[64:65], v[10:11], v[74:75], v[14:15]
	v_mul_f32_e32 v78, 0xbfb8aa3b, v119
	v_exp_f32_e32 v79, v78
	v_mul_f32_e32 v74, 0x45800000, v76
	v_cndmask_b32_e32 v74, v76, v74, vcc
	v_pk_mul_f32 v[76:77], v[74:75], v[134:135] op_sel_hi:[0,1]
	v_pk_mul_f32 v[76:77], v[28:29], v[76:77]
	v_pk_fma_f32 v[72:73], v[80:81], v[104:105], v[72:73] op_sel_hi:[0,1,1]
	v_pk_mul_f32 v[76:77], v[60:61], v[76:77]
	v_pk_mul_f32 v[60:61], v[74:75], v[126:127] op_sel_hi:[0,1]
	v_pk_mul_f32 v[60:61], v[30:31], v[60:61]
	v_pk_fma_f32 v[64:65], v[80:81], v[84:85], v[64:65] op_sel_hi:[0,1,1]
	v_pk_mul_f32 v[66:67], v[66:67], v[60:61]
	v_pk_mul_f32 v[60:61], v[74:75], v[122:123] op_sel_hi:[0,1]
	v_mul_f32_e32 v75, 0xbfb8aa3b, v118
	v_exp_f32_e32 v75, v75
	v_pk_mul_f32 v[60:61], v[24:25], v[60:61]
	v_pk_mul_f32 v[64:65], v[64:65], v[86:87]
	v_pk_mul_f32 v[80:81], v[62:63], v[60:61]
	v_add_f32_e32 v75, 1.0, v75
	v_rcp_f32_e32 v78, v75
	v_add_f32_e32 v75, 1.0, v79
	v_rcp_f32_e32 v79, v75
	v_pk_mul_f32 v[60:61], v[74:75], v[116:117] op_sel_hi:[0,1]
	v_pk_mul_f32 v[60:61], v[26:27], v[60:61]
	v_pk_mul_f32 v[72:73], v[72:73], v[106:107]
	v_pk_mul_f32 v[62:63], v[78:79], v[118:119]
	v_mov_b64_e32 v[86:87], v[42:43]
	v_pk_mul_f32 v[74:75], v[62:63], v[60:61]
	v_cvt_pk_bf16_f32 v63, v64, v65
	v_lshl_add_u64 v[64:65], s[92:93], 0, v[90:91]
	v_add_co_u32_e32 v64, vcc, s14, v64
	v_cvt_pk_bf16_f32 v60, v68, v69
	v_cvt_pk_bf16_f32 v61, v72, v73
	v_cvt_pk_bf16_f32 v62, v70, v71
	v_addc_co_u32_e32 v65, vcc, 0, v65, vcc
	global_store_dwordx4 v[64:65], v[60:63], off offset:1024 sc1
	v_mov_b64_e32 v[70:71], v[34:35]
	v_lshl_add_u64 v[90:91], v[90:91], 0, s[10:11]
	v_cvt_pk_bf16_f32 v60, v76, v77
	v_cvt_pk_bf16_f32 v61, v66, v67
	v_cvt_pk_bf16_f32 v62, v80, v81
	v_cvt_pk_bf16_f32 v63, v74, v75
	global_store_dwordx4 v[64:65], v[60:63], off sc1
	v_mov_b64_e32 v[82:83], v[38:39]
	v_mov_b64_e32 v[74:75], v[46:47]
	v_mov_b64_e32 v[78:79], v[50:51]
	v_mov_b64_e32 v[62:63], v[54:55]
	v_mov_b64_e32 v[66:67], v[58:59]
	v_mov_b64_e32 v[68:69], v[32:33]
	v_mov_b64_e32 v[80:81], v[36:37]
	v_mov_b64_e32 v[84:85], v[40:41]
	v_mov_b64_e32 v[72:73], v[44:45]
	v_mov_b64_e32 v[76:77], v[48:49]
	v_mov_b64_e32 v[60:61], v[52:53]
	v_mov_b64_e32 v[64:65], v[56:57]
	s_andn2_b64 exec, exec, s[20:21]
	s_cbranch_execz .LBB0_835
